# ret_out_item staging: the three Q/K/V loads per iteration issued together with counted waits instead of load-wait-write chains
# speedup vs baseline: 1.0087x; 1.0034x over previous
; __device__ __forceinline__ void ret_out_item(const P& p, int layer, int item, char* lds) {
;     ...
;   for (int e = tid; e < 128 * 8; e += NTHR) {
;     const int j = e >> 3, c8 = (e & 7) * 8;
;     *(bf16x8*)&Qs[j * 72 + c8] = *(const bf16x8*)(z + (tok0 + j) * ZC + C_RQ + h * 64 + c8);
;     *(bf16x8*)&Ks[j * 72 + c8] = *(const bf16x8*)(z + (tok0 + j) * ZC + C_RK + h * 64 + c8);
;     const bf16x8 vv = *(const bf16x8*)(z + (tok0 + j) * ZC + C_RV + h * 64 + c8);
; #pragma unroll
;     for (int q = 0; q < 8; ++q) VT[(c8 + q) * 136 + j] = (u16)vv[q];
;   }
.LBB0_262:
	s_waitcnt vmcnt(5)
	v_ashrrev_i32_e32 v10, 3, v4
	v_ashrrev_i32_e32 v11, 31, v10
	v_lshl_add_u64 v[6:7], s[70:71], 0, v[10:11]
	v_mov_b64_e32 v[8:9], s[60:61]
	v_mad_u64_u32 v[8:9], s[6:7], v6, s9, v[8:9]
	v_mov_b32_e32 v6, v9
	v_mad_u64_u32 v[6:7], s[6:7], v7, s9, v[6:7]
	s_waitcnt vmcnt(4)
	v_and_b32_e32 v12, 56, v3
	v_mov_b32_e32 v9, v6
	v_lshl_add_u64 v[6:7], v[8:9], 0, s[92:93]
	v_lshlrev_b32_e32 v200, 1, v12
	v_lshl_add_u64 v[14:15], v[6:7], 0, v[200:201]
	global_load_dwordx4 v[6:9], v[14:15], off offset:3072
	global_load_dwordx4 v[18:21], v[14:15], off offset:3584
	v_add_co_u32_e64 v22, s[40:41], s10, v14
	s_nop 1
	v_addc_co_u32_e64 v23, s[40:41], 0, v15, s[40:41]
	global_load_dwordx4 v[22:25], v[22:23], off
	s_movk_i32 s6, 0x48
	s_waitcnt vmcnt(6)
	v_mad_u64_u32 v[16:17], s[6:7], v10, s6, v[12:13]
	v_lshl_add_u32 v5, v16, 1, 0
	v_add_u32_e32 v3, 0x800, v3
	v_lshlrev_b32_e32 v26, 1, v10
	v_mul_u32_u24_e32 v27, 0x110, v12
	v_add3_u32 v26, 0, v26, v27
	v_cmp_lt_i32_e64 s[40:41], s16, v4
	s_or_b64 s[76:77], s[40:41], s[76:77]
	s_waitcnt vmcnt(2)
	ds_write_b128 v5, v[6:9]
	s_waitcnt vmcnt(1)
	ds_write_b128 v5, v[18:21] offset:18432
	s_waitcnt vmcnt(0)
	ds_write_b16 v26, v22 offset:36864
	ds_write_b16_d16_hi v26, v22 offset:37136
	ds_write_b16 v26, v23 offset:37408
	ds_write_b16_d16_hi v26, v23 offset:37680
	ds_write_b16 v26, v24 offset:37952
	ds_write_b16_d16_hi v26, v24 offset:38224
	ds_write_b16 v26, v25 offset:38496
	ds_write_b16_d16_hi v26, v25 offset:38768
	v_add_u32_e32 v5, 0x100, v4
	v_mov_b32_e32 v4, v5
	s_andn2_b64 exec, exec, s[76:77]
	s_cbranch_execnz .LBB0_262
	s_or_b64 exec, exec, s[76:77]
	s_and_b32 s6, s33, 0xffffff3f
	s_or_b32 s6, s8, s6
	s_ashr_i32 s7, s6, 31
	s_lshl_b64 s[6:7], s[6:7], 14
	s_add_u32 s6, s18, s6
	s_addc_u32 s7, s19, s7
	s_mov_b64 s[72:73], 0
	v_mov_b32_e32 v3, v0
